# helper workgroups' row-normalisation loops paced (s_sleep 16 per two rows) to spread their streaming traffic over the chains' first half
# speedup vs baseline: 1.0009x; 1.0009x over previous
; template <class OutRow>
; __device__ __forceinline__ void h_rows_t(const float* x, const float* w, OutRow orow, int nrows, int gw, int ngw, int lane) {
;     ...
;     for (int m0 = gw; m0 < nrows; m0 += 2 * ngw) {
; #pragma unroll
;         for (int u = 0; u < 2; ++u) { const int m = m0 + (2 + u) * ngw; if (m < nrows) { const f32x4* xr = (const f32x4*)(x + (size_t)m * D) + 2 * lane;
; #pragma unroll
;             for (int j = 0; j < 4; ++j) vn[u][j] = xr[(j >> 1) * 128 + (j & 1)]; } }
.LBB0_500:
	s_sleep 16
	s_add_i32 s2, s58, s7
	s_cmpk_gt_i32 s2, 0x1fff
	s_cbranch_scc1 .LBB0_502
	global_load_dwordx4 v[34:37], v[88:89], off offset:16
	global_load_dwordx4 v[42:45], v[88:89], off
	global_load_dwordx4 v[50:53], v[88:89], off offset:2064
	global_load_dwordx4 v[58:61], v[88:89], off offset:2048

; template <class OutRow>
; __device__ __forceinline__ void h_rows_t(const float* x, const float* w, OutRow orow, int nrows, int gw, int ngw, int lane) {
;     ...
;     for (int m0 = gw; m0 < nrows; m0 += 2 * ngw) {
; #pragma unroll
;         for (int u = 0; u < 2; ++u) { const int m = m0 + (2 + u) * ngw; if (m < nrows) { const f32x4* xr = (const f32x4*)(x + (size_t)m * D) + 2 * lane;
; #pragma unroll
;             for (int j = 0; j < 4; ++j) vn[u][j] = xr[(j >> 1) * 128 + (j & 1)]; } }
.LBB0_559:
	s_sleep 16
	v_readlane_b32 s2, v252, 57
	s_add_i32 s2, s2, s39
	s_cmpk_gt_i32 s2, 0x3fff
	s_cbranch_scc1 .LBB0_561
	global_load_dwordx4 v[34:37], v[86:87], off offset:16
	global_load_dwordx4 v[42:45], v[86:87], off
	global_load_dwordx4 v[50:53], v[86:87], off offset:2064
	global_load_dwordx4 v[58:61], v[86:87], off offset:2048
